# AB + GEMM units: first-trip fragment ds_reads issued at the top of the unit header, ahead of the scheduler arithmetic
# baseline (speedup 1.0000x reference)
; #define PG8_STAGE(bufoff, gbase, voff) do { _Pragma("unroll") for (int _i = 0; _i < 2; ++_i) \
;         __builtin_amdgcn_global_load_lds((const unsigned*)((const char*)(gbase) + (voff)[_i]), (PG8_LAS unsigned*)(lds + (bufoff) + ldsw + _i * 8192), 16, 0, 0); } while (0)
; #define PG8_LDA(dst, b, h) do { _Pragma("unroll") for (int m = 0; m < 4; ++m) _Pragma("unroll") for (int k = 0; k < 2; ++k) dst[m][k] = *(const PG8_LAS bf16x8*)(lds + PG8_SA(b, h) + aoff + m * 2048 + k * 1024); } while (0)
;     __host__ __device__ bool next(int i, Unit& u) const {
;         const long L = (long)i * G + c; if (L >= nwg) return false;
;         int wgid = (int)L; { const int q = nwg / NXCD, r = nwg % NXCD, xcd = wgid % NXCD, off = wgid / NXCD; wgid = (xcd < r ? xcd * (q + 1) : r * (q + 1) + (xcd - r) * q) + off; }
;         const int nig = WGM * nN, gid = wgid / nig, fm = gid * WGM, gsz = (nM - fm) < WGM ? (nM - fm) : WGM;
;         u.pm = fm + ((wgid % nig) % gsz); u.pn = (wgid % nig) / gsz; return true;
;     }
; template <class Epi, class Sched, bool ALIGN_EPI = false, bool SP2 = false>
; __device__ __forceinline__ void gemm_phase(PG8_LAS unsigned char* lds, const Gemm g, const Sched& S, const Epi& E) {
;     ...
;     for (;;) {
;         const bool has_next = S.next(ui + 1, nxt);
;         const char* nA = has_next ? (const char*)g.A + (size_t)nxt.pm * tstep : cA; const char* nB = has_next ? (const char*)g.Bt + (size_t)nxt.pn * tstep : cB;
;         for (int t = 0; t < nt; t += 2) {
;             const bool last = (t == nt - 2);
;             const char* a1 = cA + (size_t)(t + 1) * kstep;
;             const char* a2 = last ? nA : cA + (size_t)(t + 2) * kstep; const char* b2 = last ? nB : cB + (size_t)(t + 2) * kstep;
;             const char* a3 = a2 + kstep; const char* b3 = b2 + kstep;
;             if (last && has_next) S.a_ready(nxt);
;             if constexpr (SP2) {
;             PG8_LDB(B0, 0, 0); PG8_LDB(B1, 0, 1); PG8_SCHED; PG8_LDA(At, 0, 0); PG8_STAGE(PG8_SA(1, 1), a1 + hstep, voffA);
;             PG8_WAIT_V(8); PG8_WAIT_L(0); PG8_BAR; PG8_MMA(0, 0, At, B0); PG8_MMA(0, 1, At, B1); PG8_BAR; PG8_SCHED;
;             PG8_LDA(At, 0, 1); PG8_STAGE(PG8_SB(0, 0), b2, voffB); PG8_STAGE(PG8_SB(0, 1), b2 + hstep, voffB); PG8_STAGE(PG8_SA(0, 0), a2, voffA);
;             PG8_WAIT_V(8); PG8_WAIT_L(0); PG8_BAR; PG8_MMA(1, 0, At, B0); PG8_MMA(1, 1, At, B1); PG8_BAR; PG8_SCHED;
.LBB0_162:
	v_add_u32_e32 v144, 0x10000, v147
	ds_read_b128 v[140:143], v144
	ds_read_b128 v[156:159], v144 offset:1024
	ds_read_b128 v[160:163], v144 offset:2048
	ds_read_b128 v[164:167], v144 offset:3072
	v_add_u32_e32 v144, 0x14000, v147
	ds_read_b128 v[168:171], v144
	ds_read_b128 v[172:175], v144 offset:1024
	ds_read_b128 v[192:195], v144 offset:2048
	ds_read_b128 v[196:199], v144 offset:3072
	ds_read_b128 v[200:203], v149
	ds_read_b128 v[204:207], v149 offset:1024
	ds_read_b128 v[208:211], v149 offset:2048
	ds_read_b128 v[212:215], v149 offset:3072
	ds_read_b128 v[216:219], v149 offset:4096
	ds_read_b128 v[220:223], v149 offset:5120
	ds_read_b128 v[224:227], v149 offset:6144
	ds_read_b128 v[228:231], v149 offset:7168
	s_add_i32 s26, s26, 1
	s_mul_i32 s40, s26, s53
	s_mul_hi_u32 s41, s26, s52
	s_add_i32 s41, s41, s40
	s_mul_i32 s40, s26, s52
	s_add_u32 s74, s40, s2
	s_addc_u32 s75, s41, s3
	v_mov_b64_e32 v[0:1], 0x300
	v_cmp_lt_i64_e64 s[40:41], s[74:75], v[0:1]
	v_mov_b64_e32 v[0:1], 0x2ff
	v_cmp_gt_i64_e32 vcc, s[74:75], v[0:1]
	s_cbranch_vccnz .LBB0_164
	s_ashr_i32 s44, s74, 31
	s_lshr_b32 s44, s44, 29
	s_add_i32 s44, s74, s44
	s_ashr_i32 s45, s44, 3
	s_and_b32 s44, s44, -8
	s_sub_i32 s44, s74, s44
	s_cmp_lt_i32 s44, 0
	s_movk_i32 s46, 0x61
	s_cselect_b32 s46, s46, 0x60
	s_mul_i32 s44, s44, s46
	s_add_i32 s44, s44, s45
	s_mul_hi_i32 s45, s44, 0x2aaaaaab
	s_lshr_b32 s46, s45, 31
	s_ashr_i32 s45, s45, 5
	s_add_i32 s45, s45, s46
	s_lshl_b32 s46, s45, 3
	s_sub_i32 s47, 32, s46
	s_min_i32 s47, s47, 8
	s_mulk_i32 s45, 0xc0
	s_sub_i32 s45, s44, s45
	s_lshr_b32 s44, s45, 3
	s_and_b32 s45, s45, 7
	s_add_i32 s46, s46, s45
.LBB0_164:
	s_ashr_i32 s47, s46, 31
	s_lshl_b64 s[58:59], s[46:47], 20
	s_add_u32 s74, s12, s58
	s_addc_u32 s75, s13, s59
	s_and_b64 s[58:59], s[40:41], exec
	s_cselect_b32 s47, s75, s43
	s_cselect_b32 s55, s74, s42
	s_ashr_i32 s45, s44, 31
	s_lshl_b64 s[58:59], s[44:45], 20
	v_readlane_b32 s68, v255, 52
	v_readlane_b32 s69, v255, 53
	s_add_u32 s76, s68, s58
	s_addc_u32 s77, s69, s59
	s_and_b64 s[58:59], s[40:41], exec
	s_cselect_b32 s45, s77, s79
	s_cselect_b32 s58, s76, s78
	s_add_u32 s42, s42, 0x80080
	s_addc_u32 s43, s43, 0
	s_add_u32 s59, s78, 0x100
	v_mov_b32_e32 v0, 0
	s_addc_u32 s63, s79, 0
	s_mov_b32 s71, -2
	s_add_u32 s68, s42, 0xfff80080
	s_addc_u32 s69, s43, -1
	s_add_i32 s82, 0, 0x10000
	s_cmp_eq_u32 s71, 28
	s_cselect_b32 s81, s47, s69
	s_cselect_b32 s80, s55, s68
	s_cselect_b32 s79, s45, s63
	s_cselect_b32 s78, s58, s59
	s_add_i32 s83, 0, 0x14000
	v_lshl_add_u64 v[150:151], s[42:43], 0, v[136:137]
	s_add_i32 m0, s14, 0xc000
	global_load_lds_dwordx4 v[150:151], off
	v_lshl_add_u64 v[150:151], s[42:43], 0, v[138:139]
	s_add_i32 m0, s14, 0xe000
	s_nop 0
	global_load_lds_dwordx4 v[150:151], off
	s_waitcnt vmcnt(8)
	s_waitcnt lgkmcnt(0)
	s_setprio 1
	s_barrier
	v_mfma_f32_16x16x32_bf16 v[124:127], v[140:143], v[200:203], 0
	v_mfma_f32_16x16x32_bf16 v[120:123], v[160:163], v[200:203], 0
	v_mfma_f32_16x16x32_bf16 v[108:111], v[140:143], v[208:211], 0
	v_mfma_f32_16x16x32_bf16 v[104:107], v[160:163], v[208:211], 0
	v_mfma_f32_16x16x32_bf16 v[92:95], v[140:143], v[216:219], 0
	v_mfma_f32_16x16x32_bf16 v[88:91], v[160:163], v[216:219], 0
	v_mfma_f32_16x16x32_bf16 v[76:79], v[140:143], v[224:227], 0
	v_mfma_f32_16x16x32_bf16 v[72:75], v[160:163], v[224:227], 0
	v_mfma_f32_16x16x32_bf16 v[124:127], v[156:159], v[204:207], v[124:127]
	v_mfma_f32_16x16x32_bf16 v[120:123], v[164:167], v[204:207], v[120:123]
	v_mfma_f32_16x16x32_bf16 v[108:111], v[156:159], v[212:215], v[108:111]
	v_mfma_f32_16x16x32_bf16 v[104:107], v[164:167], v[212:215], v[104:107]
	v_mfma_f32_16x16x32_bf16 v[92:95], v[156:159], v[220:223], v[92:95]
	v_mfma_f32_16x16x32_bf16 v[88:91], v[164:167], v[220:223], v[88:91]
	v_mfma_f32_16x16x32_bf16 v[76:79], v[156:159], v[228:231], v[76:79]
	v_mfma_f32_16x16x32_bf16 v[72:75], v[164:167], v[228:231], v[72:75]
	v_mfma_f32_16x16x32_bf16 v[116:119], v[168:171], v[200:203], 0
	v_mfma_f32_16x16x32_bf16 v[112:115], v[192:195], v[200:203], 0
	v_mfma_f32_16x16x32_bf16 v[100:103], v[168:171], v[208:211], 0
	v_mfma_f32_16x16x32_bf16 v[96:99], v[192:195], v[208:211], 0
	v_mfma_f32_16x16x32_bf16 v[84:87], v[168:171], v[216:219], 0
	v_mfma_f32_16x16x32_bf16 v[80:83], v[192:195], v[216:219], 0
	v_mfma_f32_16x16x32_bf16 v[68:71], v[168:171], v[224:227], 0
	v_mfma_f32_16x16x32_bf16 v[64:67], v[192:195], v[224:227], 0
	v_mfma_f32_16x16x32_bf16 v[116:119], v[172:175], v[204:207], v[116:119]
	v_mfma_f32_16x16x32_bf16 v[112:115], v[196:199], v[204:207], v[112:115]
	v_mfma_f32_16x16x32_bf16 v[100:103], v[172:175], v[212:215], v[100:103]
	v_mfma_f32_16x16x32_bf16 v[96:99], v[196:199], v[212:215], v[96:99]
	v_mfma_f32_16x16x32_bf16 v[84:87], v[172:175], v[220:223], v[84:87]
	v_mfma_f32_16x16x32_bf16 v[80:83], v[196:199], v[220:223], v[80:83]
	v_mfma_f32_16x16x32_bf16 v[68:71], v[172:175], v[228:231], v[68:71]
	v_mfma_f32_16x16x32_bf16 v[64:67], v[196:199], v[228:231], v[64:67]
	s_barrier
	s_setprio 0
	s_add_i32 s68, s82, s0
	v_lshl_add_u64 v[150:151], s[78:79], 0, v[152:153]
	s_mov_b32 m0, s68
	ds_read_b128 v[200:203], v149 offset:16384
	ds_read_b128 v[204:207], v149 offset:17408
	ds_read_b128 v[208:211], v149 offset:18432
	ds_read_b128 v[212:215], v149 offset:19456
	ds_read_b128 v[216:219], v149 offset:20480
	ds_read_b128 v[220:223], v149 offset:21504
	ds_read_b128 v[224:227], v149 offset:22528
	ds_read_b128 v[228:231], v149 offset:23552
	global_load_lds_dwordx4 v[150:151], off
	s_add_i32 m0, s68, 0x2000
	s_add_u32 s68, s78, 0x80000
	v_lshl_add_u64 v[182:183], s[78:79], 0, v[128:129]
	s_addc_u32 s69, s79, 0
	s_add_i32 s82, s83, s0
	global_load_lds_dwordx4 v[182:183], off
	v_lshl_add_u64 v[184:185], s[68:69], 0, v[152:153]
	s_mov_b32 m0, s82
	v_lshl_add_u64 v[188:189], s[80:81], 0, v[130:131]
	global_load_lds_dwordx4 v[184:185], off
	v_lshl_add_u64 v[184:185], s[68:69], 0, v[128:129]
	s_add_i32 m0, s82, 0x2000
	s_nop 0
	global_load_lds_dwordx4 v[184:185], off
	v_lshl_add_u64 v[184:185], s[80:81], 0, v[132:133]
	s_mov_b32 m0, s14
	s_nop 0
	global_load_lds_dwordx4 v[184:185], off
	s_mov_b32 m0, s15
	s_nop 0
	global_load_lds_dwordx4 v[188:189], off
	s_waitcnt vmcnt(8)
	s_waitcnt lgkmcnt(0)
	s_setprio 1
	s_barrier
; #define PG8_STAGE(bufoff, gbase, voff) do { _Pragma("unroll") for (int _i = 0; _i < 2; ++_i) \
;         __builtin_amdgcn_global_load_lds((const unsigned*)((const char*)(gbase) + (voff)[_i]), (PG8_LAS unsigned*)(lds + (bufoff) + ldsw + _i * 8192), 16, 0, 0); } while (0)
; #define PG8_LDA(dst, b, h) do { _Pragma("unroll") for (int m = 0; m < 4; ++m) _Pragma("unroll") for (int k = 0; k < 2; ++k) dst[m][k] = *(const PG8_LAS bf16x8*)(lds + PG8_SA(b, h) + aoff + m * 2048 + k * 1024); } while (0)
; #define PG8_LDB(dst, b, h) do { _Pragma("unroll") for (int n = 0; n < 2; ++n) _Pragma("unroll") for (int k = 0; k < 2; ++k) dst[n][k] = *(const PG8_LAS bf16x8*)(lds + PG8_SB(b, h) + boff + n * 2048 + k * 1024); } while (0)
; #define PG8_MMA(ai, bj, At, Bt) do { __builtin_amdgcn_s_setprio(1); _Pragma("unroll") for (int m = 0; m < 4; ++m) _Pragma("unroll") for (int n = 0; n < 2; ++n) _Pragma("unroll") for (int k = 0; k < 2; ++k) \
;         acc[ai][bj][m][n] = __builtin_amdgcn_mfma_f32_16x16x32_bf16(Bt[n][k], At[m][k], acc[ai][bj][m][n], 0, 0, 0); __builtin_amdgcn_s_setprio(0); } while (0)
; #define PG8_WAIT_V(n) asm volatile("s_waitcnt vmcnt(" #n ")" ::: "memory")
; #define PG8_WAIT_L(n) asm volatile("s_waitcnt lgkmcnt(" #n ")" ::: "memory")
; #define PG8_BAR __builtin_amdgcn_s_barrier()
; #define PG8_SCHED __builtin_amdgcn_sched_barrier(0)
; template <class Epi, class Sched, bool ALIGN_EPI = false, bool SP2 = false>
; __device__ __forceinline__ void gemm_phase(PG8_LAS unsigned char* lds, const Gemm g, const Sched& S, const Epi& E) {
;     ...
;             PG8_WAIT_V(8); PG8_WAIT_L(0); PG8_BAR; PG8_MMA(1, 0, At, B0); PG8_MMA(1, 1, At, B1); PG8_BAR; PG8_SCHED;
;             PG8_LDB(B0, 1, 0); PG8_LDB(B1, 1, 1); PG8_SCHED; PG8_LDA(At, 1, 0); PG8_STAGE(PG8_SA(0, 1), a2 + hstep, voffA);
;             PG8_WAIT_V(8); PG8_WAIT_L(0); PG8_BAR; PG8_MMA(0, 0, At, B0); PG8_MMA(0, 1, At, B1); PG8_BAR; PG8_SCHED;
	v_mfma_f32_16x16x32_bf16 v[60:63], v[140:143], v[200:203], 0
	v_mfma_f32_16x16x32_bf16 v[56:59], v[160:163], v[200:203], 0
	v_mfma_f32_16x16x32_bf16 v[44:47], v[140:143], v[208:211], 0
	v_mfma_f32_16x16x32_bf16 v[40:43], v[160:163], v[208:211], 0
	v_mfma_f32_16x16x32_bf16 v[28:31], v[140:143], v[216:219], 0
	v_mfma_f32_16x16x32_bf16 v[24:27], v[160:163], v[216:219], 0
	v_mfma_f32_16x16x32_bf16 v[12:15], v[140:143], v[224:227], 0
	v_mfma_f32_16x16x32_bf16 v[8:11], v[160:163], v[224:227], 0
	v_mfma_f32_16x16x32_bf16 v[60:63], v[156:159], v[204:207], v[60:63]
	v_mfma_f32_16x16x32_bf16 v[56:59], v[164:167], v[204:207], v[56:59]
	v_mfma_f32_16x16x32_bf16 v[44:47], v[156:159], v[212:215], v[44:47]
	v_mfma_f32_16x16x32_bf16 v[40:43], v[164:167], v[212:215], v[40:43]
	v_mfma_f32_16x16x32_bf16 v[28:31], v[156:159], v[220:223], v[28:31]
	v_mfma_f32_16x16x32_bf16 v[24:27], v[164:167], v[220:223], v[24:27]
	v_mfma_f32_16x16x32_bf16 v[12:15], v[156:159], v[228:231], v[12:15]
	v_mfma_f32_16x16x32_bf16 v[8:11], v[164:167], v[228:231], v[8:11]
	v_mfma_f32_16x16x32_bf16 v[52:55], v[168:171], v[200:203], 0
	v_mfma_f32_16x16x32_bf16 v[48:51], v[192:195], v[200:203], 0
	v_mfma_f32_16x16x32_bf16 v[36:39], v[168:171], v[208:211], 0
	v_mfma_f32_16x16x32_bf16 v[32:35], v[192:195], v[208:211], 0
	v_mfma_f32_16x16x32_bf16 v[20:23], v[168:171], v[216:219], 0
	v_mfma_f32_16x16x32_bf16 v[16:19], v[192:195], v[216:219], 0
	v_mfma_f32_16x16x32_bf16 v[4:7], v[168:171], v[224:227], 0
	v_mfma_f32_16x16x32_bf16 v[0:3], v[192:195], v[224:227], 0
	v_mfma_f32_16x16x32_bf16 v[52:55], v[172:175], v[204:207], v[52:55]
	v_mfma_f32_16x16x32_bf16 v[48:51], v[196:199], v[204:207], v[48:51]
	v_mfma_f32_16x16x32_bf16 v[36:39], v[172:175], v[212:215], v[36:39]
	v_mfma_f32_16x16x32_bf16 v[32:35], v[196:199], v[212:215], v[32:35]
	v_mfma_f32_16x16x32_bf16 v[20:23], v[172:175], v[220:223], v[20:23]
	v_mfma_f32_16x16x32_bf16 v[16:19], v[196:199], v[220:223], v[16:19]
	v_mfma_f32_16x16x32_bf16 v[4:7], v[172:175], v[228:231], v[4:7]
	v_mfma_f32_16x16x32_bf16 v[0:3], v[196:199], v[228:231], v[0:3]
	s_barrier
	s_setprio 0
	v_add_u32_e32 v144, s93, v147
	s_add_i32 s82, 0, 0x1c000
	ds_read_b128 v[140:143], v144
	ds_read_b128 v[156:159], v144 offset:1024
	ds_read_b128 v[160:163], v144 offset:2048
	ds_read_b128 v[164:167], v144 offset:3072
	v_add_u32_e32 v144, s82, v147
	ds_read_b128 v[168:171], v144
	ds_read_b128 v[172:175], v144 offset:1024
	ds_read_b128 v[192:195], v144 offset:2048
	ds_read_b128 v[196:199], v144 offset:3072
	s_add_u32 s68, s80, 0x80000
	s_addc_u32 s69, s81, 0
	s_mov_b32 m0, s16
	v_lshl_add_u64 v[190:191], s[68:69], 0, v[132:133]
	ds_read_b128 v[200:203], v149 offset:32768
	ds_read_b128 v[204:207], v149 offset:33792
	ds_read_b128 v[208:211], v149 offset:34816
	ds_read_b128 v[212:215], v149 offset:35840
	ds_read_b128 v[216:219], v149 offset:36864
	ds_read_b128 v[220:223], v149 offset:37888
	ds_read_b128 v[224:227], v149 offset:38912
	ds_read_b128 v[228:231], v149 offset:39936
	global_load_lds_dwordx4 v[190:191], off
	v_lshl_add_u64 v[190:191], s[68:69], 0, v[130:131]
	s_mov_b32 m0, s17
	s_nop 0
	global_load_lds_dwordx4 v[190:191], off
	s_waitcnt vmcnt(8)
	s_waitcnt lgkmcnt(0)
	s_setprio 1
	s_barrier
	v_mfma_f32_16x16x32_bf16 v[124:127], v[140:143], v[200:203], v[124:127]
	v_mfma_f32_16x16x32_bf16 v[120:123], v[160:163], v[200:203], v[120:123]
	v_mfma_f32_16x16x32_bf16 v[108:111], v[140:143], v[208:211], v[108:111]
	v_mfma_f32_16x16x32_bf16 v[104:107], v[160:163], v[208:211], v[104:107]
	v_mfma_f32_16x16x32_bf16 v[92:95], v[140:143], v[216:219], v[92:95]
	v_mfma_f32_16x16x32_bf16 v[88:91], v[160:163], v[216:219], v[88:91]
	v_mfma_f32_16x16x32_bf16 v[76:79], v[140:143], v[224:227], v[76:79]
	v_mfma_f32_16x16x32_bf16 v[72:75], v[160:163], v[224:227], v[72:75]
	v_mfma_f32_16x16x32_bf16 v[124:127], v[156:159], v[204:207], v[124:127]
	v_mfma_f32_16x16x32_bf16 v[120:123], v[164:167], v[204:207], v[120:123]
	v_mfma_f32_16x16x32_bf16 v[108:111], v[156:159], v[212:215], v[108:111]
	v_mfma_f32_16x16x32_bf16 v[104:107], v[164:167], v[212:215], v[104:107]
	v_mfma_f32_16x16x32_bf16 v[92:95], v[156:159], v[220:223], v[92:95]
	v_mfma_f32_16x16x32_bf16 v[88:91], v[164:167], v[220:223], v[88:91]
	v_mfma_f32_16x16x32_bf16 v[76:79], v[156:159], v[228:231], v[76:79]
	v_mfma_f32_16x16x32_bf16 v[72:75], v[164:167], v[228:231], v[72:75]
	v_mfma_f32_16x16x32_bf16 v[116:119], v[168:171], v[200:203], v[116:119]
	v_mfma_f32_16x16x32_bf16 v[112:115], v[192:195], v[200:203], v[112:115]
	v_mfma_f32_16x16x32_bf16 v[100:103], v[168:171], v[208:211], v[100:103]
	v_mfma_f32_16x16x32_bf16 v[96:99], v[192:195], v[208:211], v[96:99]
	v_mfma_f32_16x16x32_bf16 v[84:87], v[168:171], v[216:219], v[84:87]
	v_mfma_f32_16x16x32_bf16 v[80:83], v[192:195], v[216:219], v[80:83]
	v_mfma_f32_16x16x32_bf16 v[68:71], v[168:171], v[224:227], v[68:71]
	v_mfma_f32_16x16x32_bf16 v[64:67], v[192:195], v[224:227], v[64:67]
	v_mfma_f32_16x16x32_bf16 v[116:119], v[172:175], v[204:207], v[116:119]
	v_mfma_f32_16x16x32_bf16 v[112:115], v[196:199], v[204:207], v[112:115]
	v_mfma_f32_16x16x32_bf16 v[100:103], v[172:175], v[212:215], v[100:103]
	v_mfma_f32_16x16x32_bf16 v[96:99], v[196:199], v[212:215], v[96:99]
	v_mfma_f32_16x16x32_bf16 v[84:87], v[172:175], v[220:223], v[84:87]
	v_mfma_f32_16x16x32_bf16 v[80:83], v[196:199], v[220:223], v[80:83]
	v_mfma_f32_16x16x32_bf16 v[68:71], v[172:175], v[228:231], v[68:71]
	v_mfma_f32_16x16x32_bf16 v[64:67], v[196:199], v[228:231], v[64:67]
	s_barrier
; #define PG8_STAGE(bufoff, gbase, voff) do { _Pragma("unroll") for (int _i = 0; _i < 2; ++_i) \
;         __builtin_amdgcn_global_load_lds((const unsigned*)((const char*)(gbase) + (voff)[_i]), (PG8_LAS unsigned*)(lds + (bufoff) + ldsw + _i * 8192), 16, 0, 0); } while (0)
; #define PG8_LDA(dst, b, h) do { _Pragma("unroll") for (int m = 0; m < 4; ++m) _Pragma("unroll") for (int k = 0; k < 2; ++k) dst[m][k] = *(const PG8_LAS bf16x8*)(lds + PG8_SA(b, h) + aoff + m * 2048 + k * 1024); } while (0)
; #define PG8_MMA(ai, bj, At, Bt) do { __builtin_amdgcn_s_setprio(1); _Pragma("unroll") for (int m = 0; m < 4; ++m) _Pragma("unroll") for (int n = 0; n < 2; ++n) _Pragma("unroll") for (int k = 0; k < 2; ++k) \
;         acc[ai][bj][m][n] = __builtin_amdgcn_mfma_f32_16x16x32_bf16(Bt[n][k], At[m][k], acc[ai][bj][m][n], 0, 0, 0); __builtin_amdgcn_s_setprio(0); } while (0)
; #define PG8_WAIT_V(n) asm volatile("s_waitcnt vmcnt(" #n ")" ::: "memory")
; #define PG8_WAIT_L(n) asm volatile("s_waitcnt lgkmcnt(" #n ")" ::: "memory")
; #define PG8_BAR __builtin_amdgcn_s_barrier()
; #define PG8_SCHED __builtin_amdgcn_sched_barrier(0)
; template <class Epi, class Sched, bool ALIGN_EPI = false, bool SP2 = false>
; __device__ __forceinline__ void gemm_phase(PG8_LAS unsigned char* lds, const Gemm g, const Sched& S, const Epi& E) {
;     ...
;             PG8_LDA(At, 1, 1); PG8_STAGE(PG8_SB(1, 0), b3, voffB); PG8_STAGE(PG8_SB(1, 1), b3 + hstep, voffB); PG8_STAGE(PG8_SA(1, 0), a3, voffA);
;             PG8_WAIT_V(8); PG8_WAIT_L(0); PG8_BAR; PG8_MMA(1, 0, At, B0); PG8_MMA(1, 1, At, B1); PG8_BAR; PG8_SCHED;
	s_setprio 0
	s_add_i32 s68, s93, s0
	v_lshl_add_u64 v[150:151], v[150:151], 0, s[18:19]
	s_mov_b32 m0, s68
	ds_read_b128 v[200:203], v149 offset:49152
	ds_read_b128 v[204:207], v149 offset:50176
	ds_read_b128 v[208:211], v149 offset:51200
	ds_read_b128 v[212:215], v149 offset:52224
	ds_read_b128 v[216:219], v149 offset:53248
	ds_read_b128 v[220:223], v149 offset:54272
	ds_read_b128 v[224:227], v149 offset:55296
	ds_read_b128 v[228:231], v149 offset:56320
	global_load_lds_dwordx4 v[150:151], off
	s_add_i32 m0, s68, 0x2000
	s_add_u32 s68, s78, 0x80080
	v_lshl_add_u64 v[150:151], v[182:183], 0, s[18:19]
	s_addc_u32 s69, s79, 0
	s_add_i32 s78, s82, s0
	global_load_lds_dwordx4 v[150:151], off
	v_lshl_add_u64 v[150:151], s[68:69], 0, v[152:153]
	s_mov_b32 m0, s78
	s_nop 0
	global_load_lds_dwordx4 v[150:151], off
	v_lshl_add_u64 v[150:151], s[68:69], 0, v[128:129]
	s_add_i32 m0, s78, 0x2000
	s_nop 0
	global_load_lds_dwordx4 v[150:151], off
	v_lshl_add_u64 v[150:151], v[184:185], 0, s[18:19]
	s_mov_b32 m0, s22
	s_nop 0
	global_load_lds_dwordx4 v[150:151], off
	v_lshl_add_u64 v[150:151], v[188:189], 0, s[18:19]
	s_mov_b32 m0, s23
	s_nop 0
	global_load_lds_dwordx4 v[150:151], off
	s_waitcnt vmcnt(8)
	s_waitcnt lgkmcnt(0)
	s_setprio 1
	s_barrier
	v_mfma_f32_16x16x32_bf16 v[60:63], v[140:143], v[200:203], v[60:63]
	v_mfma_f32_16x16x32_bf16 v[56:59], v[160:163], v[200:203], v[56:59]
	v_mfma_f32_16x16x32_bf16 v[44:47], v[140:143], v[208:211], v[44:47]
	v_mfma_f32_16x16x32_bf16 v[40:43], v[160:163], v[208:211], v[40:43]
	v_mfma_f32_16x16x32_bf16 v[28:31], v[140:143], v[216:219], v[28:31]
	v_mfma_f32_16x16x32_bf16 v[24:27], v[160:163], v[216:219], v[24:27]
	v_mfma_f32_16x16x32_bf16 v[12:15], v[140:143], v[224:227], v[12:15]
	v_mfma_f32_16x16x32_bf16 v[8:11], v[160:163], v[224:227], v[8:11]
	v_mfma_f32_16x16x32_bf16 v[60:63], v[156:159], v[204:207], v[60:63]
	v_mfma_f32_16x16x32_bf16 v[56:59], v[164:167], v[204:207], v[56:59]
	v_mfma_f32_16x16x32_bf16 v[44:47], v[156:159], v[212:215], v[44:47]
	v_mfma_f32_16x16x32_bf16 v[40:43], v[164:167], v[212:215], v[40:43]
	v_mfma_f32_16x16x32_bf16 v[28:31], v[156:159], v[220:223], v[28:31]
	v_mfma_f32_16x16x32_bf16 v[24:27], v[164:167], v[220:223], v[24:27]
	v_mfma_f32_16x16x32_bf16 v[12:15], v[156:159], v[228:231], v[12:15]
	v_mfma_f32_16x16x32_bf16 v[8:11], v[164:167], v[228:231], v[8:11]
	v_mfma_f32_16x16x32_bf16 v[52:55], v[168:171], v[200:203], v[52:55]
	v_mfma_f32_16x16x32_bf16 v[48:51], v[192:195], v[200:203], v[48:51]
	v_mfma_f32_16x16x32_bf16 v[36:39], v[168:171], v[208:211], v[36:39]
	v_mfma_f32_16x16x32_bf16 v[32:35], v[192:195], v[208:211], v[32:35]
	v_mfma_f32_16x16x32_bf16 v[20:23], v[168:171], v[216:219], v[20:23]
	v_mfma_f32_16x16x32_bf16 v[16:19], v[192:195], v[216:219], v[16:19]
	v_mfma_f32_16x16x32_bf16 v[4:7], v[168:171], v[224:227], v[4:7]
	v_mfma_f32_16x16x32_bf16 v[0:3], v[192:195], v[224:227], v[0:3]
	v_mfma_f32_16x16x32_bf16 v[52:55], v[172:175], v[204:207], v[52:55]
	v_mfma_f32_16x16x32_bf16 v[48:51], v[196:199], v[204:207], v[48:51]
	v_mfma_f32_16x16x32_bf16 v[36:39], v[172:175], v[212:215], v[36:39]
	v_mfma_f32_16x16x32_bf16 v[32:35], v[196:199], v[212:215], v[32:35]
	v_mfma_f32_16x16x32_bf16 v[20:23], v[172:175], v[220:223], v[20:23]
	v_mfma_f32_16x16x32_bf16 v[16:19], v[196:199], v[220:223], v[16:19]
	v_mfma_f32_16x16x32_bf16 v[4:7], v[172:175], v[228:231], v[4:7]
	v_mfma_f32_16x16x32_bf16 v[0:3], v[196:199], v[228:231], v[0:3]
	s_barrier
	s_setprio 0
	s_add_i32 s71, s71, 2
	s_add_u32 s42, s42, 0x100
	s_addc_u32 s43, s43, 0
	s_add_u32 s59, s59, 0x100
	s_addc_u32 s63, s63, 0
	s_cmp_gt_u32 s71, 29
	s_cbranch_scc1 .Lpeel_exit_165

;     __host__ __device__ bool next(int i, Unit& u) const {
;         const long L = (long)i * G + c; if (L >= nwg) return false;
;         int wgid = (int)L; { const int q = nwg / NXCD, r = nwg % NXCD, xcd = wgid % NXCD, off = wgid / NXCD; wgid = (xcd < r ? xcd * (q + 1) : r * (q + 1) + (xcd - r) * q) + off; }
;         const int nig = WGM * nN, gid = wgid / nig, fm = gid * WGM, gsz = (nM - fm) < WGM ? (nM - fm) : WGM;
;         u.pm = fm + ((wgid % nig) % gsz); u.pn = (wgid % nig) / gsz; return true;
;     }
; template <class Epi, class Sched, bool ALIGN_EPI = false, bool SP2 = false>
; __device__ __forceinline__ void gemm_phase(PG8_LAS unsigned char* lds, const Gemm g, const Sched& S, const Epi& E) {
;     ...
;         const bool has_next = S.next(ui + 1, nxt);
;         const char* nA = has_next ? (const char*)g.A + (size_t)nxt.pm * tstep : cA; const char* nB = has_next ? (const char*)g.Bt + (size_t)nxt.pn * tstep : cB;
;         for (int t = 0; t < nt; t += 2) {
;             const bool last = (t == nt - 2);
;             const char* a1 = cA + (size_t)(t + 1) * kstep;
;             const char* a2 = last ? nA : cA + (size_t)(t + 2) * kstep; const char* b2 = last ? nB : cB + (size_t)(t + 2) * kstep;
;             const char* a3 = a2 + kstep; const char* b3 = b2 + kstep;
;             if (last && has_next) S.a_ready(nxt);
.LBB0_207:
	v_add_u32_e32 v146, 0x10000, v149
	ds_read_b128 v[138:141], v146
	ds_read_b128 v[142:145], v146 offset:1024
	ds_read_b128 v[156:159], v146 offset:2048
	ds_read_b128 v[160:163], v146 offset:3072
	v_add_u32_e32 v146, 0x14000, v149
	ds_read_b128 v[164:167], v146
	ds_read_b128 v[168:171], v146 offset:1024
	ds_read_b128 v[172:175], v146 offset:2048
	ds_read_b128 v[192:195], v146 offset:3072
	ds_read_b128 v[196:199], v151
	ds_read_b128 v[200:203], v151 offset:1024
	ds_read_b128 v[204:207], v151 offset:2048
	ds_read_b128 v[208:211], v151 offset:3072
	ds_read_b128 v[212:215], v151 offset:4096
	ds_read_b128 v[216:219], v151 offset:5120
	ds_read_b128 v[220:223], v151 offset:6144
	ds_read_b128 v[224:227], v151 offset:7168
	s_add_i32 s59, s59, 1
	s_mul_i32 s42, s59, s53
	s_mul_hi_u32 s43, s59, s52
	s_add_i32 s43, s43, s42
	s_mul_i32 s42, s59, s52
	s_add_u32 s42, s42, s2
	s_addc_u32 s43, s43, s3
	s_waitcnt lgkmcnt(0)
	v_mov_b64_e32 v[0:1], 0x100
	v_cmp_lt_i64_e64 s[44:45], s[42:43], v[0:1]
	v_mov_b64_e32 v[0:1], 0xff
	v_cmp_gt_i64_e32 vcc, s[42:43], v[0:1]
	s_cbranch_vccnz .LBB0_213
	s_ashr_i32 s16, s42, 31
	s_lshr_b32 s16, s16, 29
	s_add_i32 s16, s42, s16
	s_and_b32 s43, s16, -8
	s_sub_i32 s49, s42, s43
	s_cmp_gt_i32 s49, -1
	s_mov_b64 s[42:43], -1
	s_cbranch_scc0 .LBB0_210
	s_lshl_b32 s82, s49, 5
	s_mov_b64 s[42:43], 0

; #define PG8_STAGE(bufoff, gbase, voff) do { _Pragma("unroll") for (int _i = 0; _i < 2; ++_i) \
;         __builtin_amdgcn_global_load_lds((const unsigned*)((const char*)(gbase) + (voff)[_i]), (PG8_LAS unsigned*)(lds + (bufoff) + ldsw + _i * 8192), 16, 0, 0); } while (0)
; #define PG8_LDA(dst, b, h) do { _Pragma("unroll") for (int m = 0; m < 4; ++m) _Pragma("unroll") for (int k = 0; k < 2; ++k) dst[m][k] = *(const PG8_LAS bf16x8*)(lds + PG8_SA(b, h) + aoff + m * 2048 + k * 1024); } while (0)
; #define PG8_LDB(dst, b, h) do { _Pragma("unroll") for (int n = 0; n < 2; ++n) _Pragma("unroll") for (int k = 0; k < 2; ++k) dst[n][k] = *(const PG8_LAS bf16x8*)(lds + PG8_SB(b, h) + boff + n * 2048 + k * 1024); } while (0)
; #define PG8_MMA(ai, bj, At, Bt) do { __builtin_amdgcn_s_setprio(1); _Pragma("unroll") for (int m = 0; m < 4; ++m) _Pragma("unroll") for (int n = 0; n < 2; ++n) _Pragma("unroll") for (int k = 0; k < 2; ++k) \
;         acc[ai][bj][m][n] = __builtin_amdgcn_mfma_f32_16x16x32_bf16(Bt[n][k], At[m][k], acc[ai][bj][m][n], 0, 0, 0); __builtin_amdgcn_s_setprio(0); } while (0)
; #define PG8_WAIT_V(n) asm volatile("s_waitcnt vmcnt(" #n ")" ::: "memory")
; #define PG8_WAIT_L(n) asm volatile("s_waitcnt lgkmcnt(" #n ")" ::: "memory")
; #define PG8_BAR __builtin_amdgcn_s_barrier()
; #define PG8_SCHED __builtin_amdgcn_sched_barrier(0)
; template <class Epi, class Sched, bool ALIGN_EPI = false, bool SP2 = false>
; __device__ __forceinline__ void gemm_phase(PG8_LAS unsigned char* lds, const Gemm g, const Sched& S, const Epi& E) {
;     ...
;             if (last && has_next) S.a_ready(nxt);
;             if constexpr (SP2) {
;             PG8_LDB(B0, 0, 0); PG8_LDB(B1, 0, 1); PG8_SCHED; PG8_LDA(At, 0, 0); PG8_STAGE(PG8_SA(1, 1), a1 + hstep, voffA);
;             PG8_WAIT_V(8); PG8_WAIT_L(0); PG8_BAR; PG8_MMA(0, 0, At, B0); PG8_MMA(0, 1, At, B1); PG8_BAR; PG8_SCHED;
;             PG8_LDA(At, 0, 1); PG8_STAGE(PG8_SB(0, 0), b2, voffB); PG8_STAGE(PG8_SB(0, 1), b2 + hstep, voffB); PG8_STAGE(PG8_SA(0, 0), a2, voffA);
;             PG8_WAIT_V(8); PG8_WAIT_L(0); PG8_BAR; PG8_MMA(1, 0, At, B0); PG8_MMA(1, 1, At, B1); PG8_BAR; PG8_SCHED;
.LBB0_217:
	s_add_u32 s44, s86, 0x80
	s_addc_u32 s45, s87, 0
	s_add_u32 s86, s46, 0x100
	v_mov_b32_e32 v0, 0
	s_addc_u32 s87, s47, 0
	s_mov_b32 s46, 0
	s_add_i32 vcc_lo, s46, 2
	s_add_u32 s68, s44, 0x80
	s_addc_u32 s47, s45, 0
	s_add_i32 vcc_hi, 0, 0x10000
	s_cmp_eq_u32 s15, s46
	s_cselect_b32 s47, s83, s47
	s_cselect_b32 s46, s82, s68
	s_cselect_b32 s69, s85, s87
	s_cselect_b32 s68, s84, s86
	s_add_i32 s96, 0, 0x14000
	v_lshl_add_u64 v[146:147], s[44:45], 0, v[134:135]
	s_add_i32 m0, s54, 0xc000
	global_load_lds_dwordx4 v[146:147], off
	v_lshl_add_u64 v[146:147], s[44:45], 0, v[136:137]
	s_add_i32 m0, s54, 0xe000
	s_nop 0
	global_load_lds_dwordx4 v[146:147], off
	s_waitcnt vmcnt(8)
	s_waitcnt lgkmcnt(0)
	s_setprio 1
	s_barrier
	v_mfma_f32_16x16x32_bf16 v[124:127], v[138:141], v[196:199], 0
	v_mfma_f32_16x16x32_bf16 v[120:123], v[156:159], v[196:199], 0
	v_mfma_f32_16x16x32_bf16 v[108:111], v[138:141], v[204:207], 0
	v_mfma_f32_16x16x32_bf16 v[104:107], v[156:159], v[204:207], 0
	v_mfma_f32_16x16x32_bf16 v[92:95], v[138:141], v[212:215], 0
	v_mfma_f32_16x16x32_bf16 v[88:91], v[156:159], v[212:215], 0
	v_mfma_f32_16x16x32_bf16 v[76:79], v[138:141], v[220:223], 0
	v_mfma_f32_16x16x32_bf16 v[72:75], v[156:159], v[220:223], 0
	v_mfma_f32_16x16x32_bf16 v[124:127], v[142:145], v[200:203], v[124:127]
	v_mfma_f32_16x16x32_bf16 v[120:123], v[160:163], v[200:203], v[120:123]
	v_mfma_f32_16x16x32_bf16 v[108:111], v[142:145], v[208:211], v[108:111]
	v_mfma_f32_16x16x32_bf16 v[104:107], v[160:163], v[208:211], v[104:107]
	v_mfma_f32_16x16x32_bf16 v[92:95], v[142:145], v[216:219], v[92:95]
	v_mfma_f32_16x16x32_bf16 v[88:91], v[160:163], v[216:219], v[88:91]
	v_mfma_f32_16x16x32_bf16 v[76:79], v[142:145], v[224:227], v[76:79]
	v_mfma_f32_16x16x32_bf16 v[72:75], v[160:163], v[224:227], v[72:75]
	v_mfma_f32_16x16x32_bf16 v[116:119], v[164:167], v[196:199], 0
	v_mfma_f32_16x16x32_bf16 v[112:115], v[172:175], v[196:199], 0
	v_mfma_f32_16x16x32_bf16 v[100:103], v[164:167], v[204:207], 0
	v_mfma_f32_16x16x32_bf16 v[96:99], v[172:175], v[204:207], 0
	v_mfma_f32_16x16x32_bf16 v[84:87], v[164:167], v[212:215], 0
	v_mfma_f32_16x16x32_bf16 v[80:83], v[172:175], v[212:215], 0
	v_mfma_f32_16x16x32_bf16 v[68:71], v[164:167], v[220:223], 0
	v_mfma_f32_16x16x32_bf16 v[64:67], v[172:175], v[220:223], 0
	v_mfma_f32_16x16x32_bf16 v[116:119], v[168:171], v[200:203], v[116:119]
	v_mfma_f32_16x16x32_bf16 v[112:115], v[192:195], v[200:203], v[112:115]
	v_mfma_f32_16x16x32_bf16 v[100:103], v[168:171], v[208:211], v[100:103]
	v_mfma_f32_16x16x32_bf16 v[96:99], v[192:195], v[208:211], v[96:99]
	v_mfma_f32_16x16x32_bf16 v[84:87], v[168:171], v[216:219], v[84:87]
	v_mfma_f32_16x16x32_bf16 v[80:83], v[192:195], v[216:219], v[80:83]
	v_mfma_f32_16x16x32_bf16 v[68:71], v[168:171], v[224:227], v[68:71]
	v_mfma_f32_16x16x32_bf16 v[64:67], v[192:195], v[224:227], v[64:67]
	s_barrier
	s_setprio 0
	s_add_i32 vcc_hi, vcc_hi, s63
	v_lshl_add_u64 v[146:147], s[68:69], 0, v[152:153]
	s_mov_b32 m0, vcc_hi
	ds_read_b128 v[196:199], v151 offset:16384
	ds_read_b128 v[200:203], v151 offset:17408
	ds_read_b128 v[204:207], v151 offset:18432
	ds_read_b128 v[208:211], v151 offset:19456
	ds_read_b128 v[212:215], v151 offset:20480
	ds_read_b128 v[216:219], v151 offset:21504
	ds_read_b128 v[220:223], v151 offset:22528
	ds_read_b128 v[224:227], v151 offset:23552
	global_load_lds_dwordx4 v[146:147], off
	s_add_i32 m0, vcc_hi, 0x2000
	v_lshl_add_u64 v[182:183], s[68:69], 0, v[128:129]
	s_add_u32 s68, s68, s48
	s_addc_u32 s69, s69, 0
	s_add_i32 s96, s96, s63
	global_load_lds_dwordx4 v[182:183], off
	v_lshl_add_u64 v[184:185], s[68:69], 0, v[152:153]
	s_mov_b32 m0, s96
	v_lshl_add_u64 v[188:189], s[68:69], 0, v[128:129]
	global_load_lds_dwordx4 v[184:185], off
	s_add_i32 m0, s96, 0x2000
	v_lshl_add_u64 v[190:191], s[46:47], 0, v[132:133]
	global_load_lds_dwordx4 v[188:189], off
	s_mov_b32 m0, s54
	v_lshl_add_u64 v[228:229], s[46:47], 0, v[130:131]
	global_load_lds_dwordx4 v[190:191], off
	s_mov_b32 m0, s55
	s_nop 0
	global_load_lds_dwordx4 v[228:229], off
	s_waitcnt vmcnt(8)
	s_waitcnt lgkmcnt(0)
	s_setprio 1
	s_barrier
	v_mfma_f32_16x16x32_bf16 v[60:63], v[138:141], v[196:199], 0
	v_mfma_f32_16x16x32_bf16 v[56:59], v[156:159], v[196:199], 0
	v_mfma_f32_16x16x32_bf16 v[44:47], v[138:141], v[204:207], 0
	v_mfma_f32_16x16x32_bf16 v[40:43], v[156:159], v[204:207], 0
	v_mfma_f32_16x16x32_bf16 v[28:31], v[138:141], v[212:215], 0
	v_mfma_f32_16x16x32_bf16 v[24:27], v[156:159], v[212:215], 0
	v_mfma_f32_16x16x32_bf16 v[12:15], v[138:141], v[220:223], 0
	v_mfma_f32_16x16x32_bf16 v[8:11], v[156:159], v[220:223], 0
	v_mfma_f32_16x16x32_bf16 v[60:63], v[142:145], v[200:203], v[60:63]
	v_mfma_f32_16x16x32_bf16 v[56:59], v[160:163], v[200:203], v[56:59]
	v_mfma_f32_16x16x32_bf16 v[44:47], v[142:145], v[208:211], v[44:47]
	v_mfma_f32_16x16x32_bf16 v[40:43], v[160:163], v[208:211], v[40:43]
	v_mfma_f32_16x16x32_bf16 v[28:31], v[142:145], v[216:219], v[28:31]
	v_mfma_f32_16x16x32_bf16 v[24:27], v[160:163], v[216:219], v[24:27]
	v_mfma_f32_16x16x32_bf16 v[12:15], v[142:145], v[224:227], v[12:15]
	v_mfma_f32_16x16x32_bf16 v[8:11], v[160:163], v[224:227], v[8:11]
	v_mfma_f32_16x16x32_bf16 v[52:55], v[164:167], v[196:199], 0
	v_mfma_f32_16x16x32_bf16 v[48:51], v[172:175], v[196:199], 0
	v_mfma_f32_16x16x32_bf16 v[36:39], v[164:167], v[204:207], 0
	v_mfma_f32_16x16x32_bf16 v[32:35], v[172:175], v[204:207], 0
	v_mfma_f32_16x16x32_bf16 v[20:23], v[164:167], v[212:215], 0
	v_mfma_f32_16x16x32_bf16 v[16:19], v[172:175], v[212:215], 0
	v_mfma_f32_16x16x32_bf16 v[4:7], v[164:167], v[220:223], 0
	v_mfma_f32_16x16x32_bf16 v[0:3], v[172:175], v[220:223], 0
	v_mfma_f32_16x16x32_bf16 v[52:55], v[168:171], v[200:203], v[52:55]
	v_mfma_f32_16x16x32_bf16 v[48:51], v[192:195], v[200:203], v[48:51]
	v_mfma_f32_16x16x32_bf16 v[36:39], v[168:171], v[208:211], v[36:39]
	v_mfma_f32_16x16x32_bf16 v[32:35], v[192:195], v[208:211], v[32:35]
	v_mfma_f32_16x16x32_bf16 v[20:23], v[168:171], v[216:219], v[20:23]
	v_mfma_f32_16x16x32_bf16 v[16:19], v[192:195], v[216:219], v[16:19]
	v_mfma_f32_16x16x32_bf16 v[4:7], v[168:171], v[224:227], v[4:7]
	v_mfma_f32_16x16x32_bf16 v[0:3], v[192:195], v[224:227], v[0:3]
	s_barrier
; #define PG8_STAGE(bufoff, gbase, voff) do { _Pragma("unroll") for (int _i = 0; _i < 2; ++_i) \
;         __builtin_amdgcn_global_load_lds((const unsigned*)((const char*)(gbase) + (voff)[_i]), (PG8_LAS unsigned*)(lds + (bufoff) + ldsw + _i * 8192), 16, 0, 0); } while (0)
; #define PG8_LDA(dst, b, h) do { _Pragma("unroll") for (int m = 0; m < 4; ++m) _Pragma("unroll") for (int k = 0; k < 2; ++k) dst[m][k] = *(const PG8_LAS bf16x8*)(lds + PG8_SA(b, h) + aoff + m * 2048 + k * 1024); } while (0)
; #define PG8_LDB(dst, b, h) do { _Pragma("unroll") for (int n = 0; n < 2; ++n) _Pragma("unroll") for (int k = 0; k < 2; ++k) dst[n][k] = *(const PG8_LAS bf16x8*)(lds + PG8_SB(b, h) + boff + n * 2048 + k * 1024); } while (0)
; #define PG8_MMA(ai, bj, At, Bt) do { __builtin_amdgcn_s_setprio(1); _Pragma("unroll") for (int m = 0; m < 4; ++m) _Pragma("unroll") for (int n = 0; n < 2; ++n) _Pragma("unroll") for (int k = 0; k < 2; ++k) \
;         acc[ai][bj][m][n] = __builtin_amdgcn_mfma_f32_16x16x32_bf16(Bt[n][k], At[m][k], acc[ai][bj][m][n], 0, 0, 0); __builtin_amdgcn_s_setprio(0); } while (0)
; #define PG8_WAIT_V(n) asm volatile("s_waitcnt vmcnt(" #n ")" ::: "memory")
; #define PG8_WAIT_L(n) asm volatile("s_waitcnt lgkmcnt(" #n ")" ::: "memory")
; #define PG8_BAR __builtin_amdgcn_s_barrier()
; #define PG8_SCHED __builtin_amdgcn_sched_barrier(0)
; template <class Epi, class Sched, bool ALIGN_EPI = false, bool SP2 = false>
; __device__ __forceinline__ void gemm_phase(PG8_LAS unsigned char* lds, const Gemm g, const Sched& S, const Epi& E) {
;     ...
;             PG8_WAIT_V(8); PG8_WAIT_L(0); PG8_BAR; PG8_MMA(1, 0, At, B0); PG8_MMA(1, 1, At, B1); PG8_BAR; PG8_SCHED;
;             PG8_LDB(B0, 1, 0); PG8_LDB(B1, 1, 1); PG8_SCHED; PG8_LDA(At, 1, 0); PG8_STAGE(PG8_SA(0, 1), a2 + hstep, voffA);
;             PG8_WAIT_V(8); PG8_WAIT_L(0); PG8_BAR; PG8_MMA(0, 0, At, B0); PG8_MMA(0, 1, At, B1); PG8_BAR; PG8_SCHED;
;             PG8_LDA(At, 1, 1); PG8_STAGE(PG8_SB(1, 0), b3, voffB); PG8_STAGE(PG8_SB(1, 1), b3 + hstep, voffB); PG8_STAGE(PG8_SA(1, 0), a3, voffA);
;             PG8_WAIT_V(8); PG8_WAIT_L(0); PG8_BAR; PG8_MMA(1, 0, At, B0); PG8_MMA(1, 1, At, B1); PG8_BAR; PG8_SCHED;
	s_setprio 0
	v_add_u32_e32 v155, s93, v149
	s_add_i32 s68, 0, 0x1c000
	ds_read_b128 v[138:141], v155
	ds_read_b128 v[142:145], v155 offset:1024
	ds_read_b128 v[156:159], v155 offset:2048
	ds_read_b128 v[160:163], v155 offset:3072
	v_add_u32_e32 v155, s68, v149
	ds_read_b128 v[164:167], v155
	ds_read_b128 v[168:171], v155 offset:1024
	ds_read_b128 v[172:175], v155 offset:2048
	ds_read_b128 v[192:195], v155 offset:3072
	s_add_u32 s46, s46, s48
	s_addc_u32 s47, s47, 0
	s_mov_b32 m0, s34
	v_lshl_add_u64 v[230:231], s[46:47], 0, v[132:133]
	ds_read_b128 v[196:199], v151 offset:32768
	ds_read_b128 v[200:203], v151 offset:33792
	ds_read_b128 v[204:207], v151 offset:34816
	ds_read_b128 v[208:211], v151 offset:35840
	ds_read_b128 v[212:215], v151 offset:36864
	ds_read_b128 v[216:219], v151 offset:37888
	ds_read_b128 v[220:223], v151 offset:38912
	ds_read_b128 v[224:227], v151 offset:39936
	global_load_lds_dwordx4 v[230:231], off
	v_lshl_add_u64 v[230:231], s[46:47], 0, v[130:131]
	s_mov_b32 m0, s95
	s_nop 0
	global_load_lds_dwordx4 v[230:231], off
	s_waitcnt vmcnt(8)
	s_waitcnt lgkmcnt(0)
	s_setprio 1
	s_barrier
	v_mfma_f32_16x16x32_bf16 v[124:127], v[138:141], v[196:199], v[124:127]
	v_mfma_f32_16x16x32_bf16 v[120:123], v[156:159], v[196:199], v[120:123]
	v_mfma_f32_16x16x32_bf16 v[108:111], v[138:141], v[204:207], v[108:111]
	v_mfma_f32_16x16x32_bf16 v[104:107], v[156:159], v[204:207], v[104:107]
	v_mfma_f32_16x16x32_bf16 v[92:95], v[138:141], v[212:215], v[92:95]
	v_mfma_f32_16x16x32_bf16 v[88:91], v[156:159], v[212:215], v[88:91]
	v_mfma_f32_16x16x32_bf16 v[76:79], v[138:141], v[220:223], v[76:79]
	v_mfma_f32_16x16x32_bf16 v[72:75], v[156:159], v[220:223], v[72:75]
	v_mfma_f32_16x16x32_bf16 v[124:127], v[142:145], v[200:203], v[124:127]
	v_mfma_f32_16x16x32_bf16 v[120:123], v[160:163], v[200:203], v[120:123]
	v_mfma_f32_16x16x32_bf16 v[108:111], v[142:145], v[208:211], v[108:111]
	v_mfma_f32_16x16x32_bf16 v[104:107], v[160:163], v[208:211], v[104:107]
	v_mfma_f32_16x16x32_bf16 v[92:95], v[142:145], v[216:219], v[92:95]
	v_mfma_f32_16x16x32_bf16 v[88:91], v[160:163], v[216:219], v[88:91]
	v_mfma_f32_16x16x32_bf16 v[76:79], v[142:145], v[224:227], v[76:79]
	v_mfma_f32_16x16x32_bf16 v[72:75], v[160:163], v[224:227], v[72:75]
	v_mfma_f32_16x16x32_bf16 v[116:119], v[164:167], v[196:199], v[116:119]
	v_mfma_f32_16x16x32_bf16 v[112:115], v[172:175], v[196:199], v[112:115]
	v_mfma_f32_16x16x32_bf16 v[100:103], v[164:167], v[204:207], v[100:103]
	v_mfma_f32_16x16x32_bf16 v[96:99], v[172:175], v[204:207], v[96:99]
	v_mfma_f32_16x16x32_bf16 v[84:87], v[164:167], v[212:215], v[84:87]
	v_mfma_f32_16x16x32_bf16 v[80:83], v[172:175], v[212:215], v[80:83]
	v_mfma_f32_16x16x32_bf16 v[68:71], v[164:167], v[220:223], v[68:71]
	v_mfma_f32_16x16x32_bf16 v[64:67], v[172:175], v[220:223], v[64:67]
	v_mfma_f32_16x16x32_bf16 v[116:119], v[168:171], v[200:203], v[116:119]
	v_mfma_f32_16x16x32_bf16 v[112:115], v[192:195], v[200:203], v[112:115]
	v_mfma_f32_16x16x32_bf16 v[100:103], v[168:171], v[208:211], v[100:103]
	v_mfma_f32_16x16x32_bf16 v[96:99], v[192:195], v[208:211], v[96:99]
	v_mfma_f32_16x16x32_bf16 v[84:87], v[168:171], v[216:219], v[84:87]
	v_mfma_f32_16x16x32_bf16 v[80:83], v[192:195], v[216:219], v[80:83]
	v_mfma_f32_16x16x32_bf16 v[68:71], v[168:171], v[224:227], v[68:71]
	v_mfma_f32_16x16x32_bf16 v[64:67], v[192:195], v[224:227], v[64:67]
	s_barrier
	s_setprio 0
	s_add_i32 s46, s93, s63
	v_lshl_add_u64 v[146:147], v[146:147], 0, s[18:19]
	s_mov_b32 m0, s46
	ds_read_b128 v[196:199], v151 offset:49152
	ds_read_b128 v[200:203], v151 offset:50176
	ds_read_b128 v[204:207], v151 offset:51200
	ds_read_b128 v[208:211], v151 offset:52224
	ds_read_b128 v[212:215], v151 offset:53248
	ds_read_b128 v[216:219], v151 offset:54272
	ds_read_b128 v[220:223], v151 offset:55296
	ds_read_b128 v[224:227], v151 offset:56320
	global_load_lds_dwordx4 v[146:147], off
	v_lshl_add_u64 v[146:147], v[182:183], 0, s[18:19]
	s_add_i32 m0, s46, 0x2000
	s_add_i32 s46, s68, s63
	global_load_lds_dwordx4 v[146:147], off
	v_lshl_add_u64 v[146:147], v[184:185], 0, s[18:19]
	s_mov_b32 m0, s46
	s_nop 0
	global_load_lds_dwordx4 v[146:147], off
	v_lshl_add_u64 v[146:147], v[188:189], 0, s[18:19]
	s_add_i32 m0, s46, 0x2000
	s_nop 0
	global_load_lds_dwordx4 v[146:147], off
	v_lshl_add_u64 v[146:147], v[190:191], 0, s[18:19]
	s_mov_b32 m0, s0
	s_nop 0
	global_load_lds_dwordx4 v[146:147], off
	v_lshl_add_u64 v[146:147], v[228:229], 0, s[18:19]
	s_mov_b32 m0, s58
	s_nop 0
	global_load_lds_dwordx4 v[146:147], off
	s_waitcnt vmcnt(8)
	s_waitcnt lgkmcnt(0)
	s_setprio 1
	s_barrier
	v_mfma_f32_16x16x32_bf16 v[60:63], v[138:141], v[196:199], v[60:63]
	v_mfma_f32_16x16x32_bf16 v[56:59], v[156:159], v[196:199], v[56:59]
	v_mfma_f32_16x16x32_bf16 v[44:47], v[138:141], v[204:207], v[44:47]
	v_mfma_f32_16x16x32_bf16 v[40:43], v[156:159], v[204:207], v[40:43]
	v_mfma_f32_16x16x32_bf16 v[28:31], v[138:141], v[212:215], v[28:31]
	v_mfma_f32_16x16x32_bf16 v[24:27], v[156:159], v[212:215], v[24:27]
	v_mfma_f32_16x16x32_bf16 v[12:15], v[138:141], v[220:223], v[12:15]
	v_mfma_f32_16x16x32_bf16 v[8:11], v[156:159], v[220:223], v[8:11]
	v_mfma_f32_16x16x32_bf16 v[60:63], v[142:145], v[200:203], v[60:63]
	v_mfma_f32_16x16x32_bf16 v[56:59], v[160:163], v[200:203], v[56:59]
	v_mfma_f32_16x16x32_bf16 v[44:47], v[142:145], v[208:211], v[44:47]
	v_mfma_f32_16x16x32_bf16 v[40:43], v[160:163], v[208:211], v[40:43]
	v_mfma_f32_16x16x32_bf16 v[28:31], v[142:145], v[216:219], v[28:31]
	v_mfma_f32_16x16x32_bf16 v[24:27], v[160:163], v[216:219], v[24:27]
	v_mfma_f32_16x16x32_bf16 v[12:15], v[142:145], v[224:227], v[12:15]
	v_mfma_f32_16x16x32_bf16 v[8:11], v[160:163], v[224:227], v[8:11]
	v_mfma_f32_16x16x32_bf16 v[52:55], v[164:167], v[196:199], v[52:55]
	v_mfma_f32_16x16x32_bf16 v[48:51], v[172:175], v[196:199], v[48:51]
	v_mfma_f32_16x16x32_bf16 v[36:39], v[164:167], v[204:207], v[36:39]
	v_mfma_f32_16x16x32_bf16 v[32:35], v[172:175], v[204:207], v[32:35]
	v_mfma_f32_16x16x32_bf16 v[20:23], v[164:167], v[212:215], v[20:23]
	v_mfma_f32_16x16x32_bf16 v[16:19], v[172:175], v[212:215], v[16:19]
	v_mfma_f32_16x16x32_bf16 v[4:7], v[164:167], v[220:223], v[4:7]
	v_mfma_f32_16x16x32_bf16 v[0:3], v[172:175], v[220:223], v[0:3]
	v_mfma_f32_16x16x32_bf16 v[52:55], v[168:171], v[200:203], v[52:55]
	v_mfma_f32_16x16x32_bf16 v[48:51], v[192:195], v[200:203], v[48:51]
	v_mfma_f32_16x16x32_bf16 v[36:39], v[168:171], v[208:211], v[36:39]
	v_mfma_f32_16x16x32_bf16 v[32:35], v[192:195], v[208:211], v[32:35]
	v_mfma_f32_16x16x32_bf16 v[20:23], v[168:171], v[216:219], v[20:23]
	v_mfma_f32_16x16x32_bf16 v[16:19], v[192:195], v[216:219], v[16:19]
	v_mfma_f32_16x16x32_bf16 v[4:7], v[168:171], v[224:227], v[4:7]
	v_mfma_f32_16x16x32_bf16 v[0:3], v[192:195], v[224:227], v[0:3]
	s_barrier
	s_setprio 0
	s_add_u32 s44, s44, 0x100
	s_addc_u32 s45, s45, 0
	s_add_u32 s86, s86, 0x100
	s_addc_u32 s87, s87, 0
	s_cmp_ge_u32 vcc_lo, s14
	s_mov_b32 s46, vcc_lo
	s_cbranch_scc1 .Lpeel_exit_218

; #define PG8_STAGE(bufoff, gbase, voff) do { _Pragma("unroll") for (int _i = 0; _i < 2; ++_i) \
;         __builtin_amdgcn_global_load_lds((const unsigned*)((const char*)(gbase) + (voff)[_i]), (PG8_LAS unsigned*)(lds + (bufoff) + ldsw + _i * 8192), 16, 0, 0); } while (0)
; #define PG8_LDA(dst, b, h) do { _Pragma("unroll") for (int m = 0; m < 4; ++m) _Pragma("unroll") for (int k = 0; k < 2; ++k) dst[m][k] = *(const PG8_LAS bf16x8*)(lds + PG8_SA(b, h) + aoff + m * 2048 + k * 1024); } while (0)
;     __host__ __device__ bool next(int i, Unit& u) const {
;         const long L = (long)i * G + c; if (L >= nwg) return false;
;         int wgid = (int)L; { const int q = nwg / NXCD, r = nwg % NXCD, xcd = wgid % NXCD, off = wgid / NXCD; wgid = (xcd < r ? xcd * (q + 1) : r * (q + 1) + (xcd - r) * q) + off; }
;         const int nig = WGM * nN, gid = wgid / nig, fm = gid * WGM, gsz = (nM - fm) < WGM ? (nM - fm) : WGM;
;         u.pm = fm + ((wgid % nig) % gsz); u.pn = (wgid % nig) / gsz; return true;
; template <class Epi, class Sched, bool ALIGN_EPI = false, bool SP2 = false>
; __device__ __forceinline__ void gemm_phase(PG8_LAS unsigned char* lds, const Gemm g, const Sched& S, const Epi& E) {
;     ...
;         const bool has_next = S.next(ui + 1, nxt);
;         const char* nA = has_next ? (const char*)g.A + (size_t)nxt.pm * tstep : cA; const char* nB = has_next ? (const char*)g.Bt + (size_t)nxt.pn * tstep : cB;
;         for (int t = 0; t < nt; t += 2) {
;             const bool last = (t == nt - 2);
;             const char* a1 = cA + (size_t)(t + 1) * kstep;
;             const char* a2 = last ? nA : cA + (size_t)(t + 2) * kstep; const char* b2 = last ? nB : cB + (size_t)(t + 2) * kstep;
;             const char* a3 = a2 + kstep; const char* b3 = b2 + kstep;
;             if (last && has_next) S.a_ready(nxt);
;             if constexpr (SP2) {
;             PG8_LDB(B0, 0, 0); PG8_LDB(B1, 0, 1); PG8_SCHED; PG8_LDA(At, 0, 0); PG8_STAGE(PG8_SA(1, 1), a1 + hstep, voffA);
;             PG8_WAIT_V(8); PG8_WAIT_L(0); PG8_BAR; PG8_MMA(0, 0, At, B0); PG8_MMA(0, 1, At, B1); PG8_BAR; PG8_SCHED;
;             PG8_LDA(At, 0, 1); PG8_STAGE(PG8_SB(0, 0), b2, voffB); PG8_STAGE(PG8_SB(0, 1), b2 + hstep, voffB); PG8_STAGE(PG8_SA(0, 0), a2, voffA);
;             PG8_WAIT_V(8); PG8_WAIT_L(0); PG8_BAR; PG8_MMA(1, 0, At, B0); PG8_MMA(1, 1, At, B1); PG8_BAR; PG8_SCHED;
.LBB0_328:
	v_add_u32_e32 v140, 0x10000, v143
	ds_read_b128 v[146:149], v140
	ds_read_b128 v[156:159], v140 offset:1024
	ds_read_b128 v[160:163], v140 offset:2048
	ds_read_b128 v[164:167], v140 offset:3072
	v_add_u32_e32 v140, 0x14000, v143
	ds_read_b128 v[168:171], v140
	ds_read_b128 v[172:175], v140 offset:1024
	ds_read_b128 v[192:195], v140 offset:2048
	ds_read_b128 v[196:199], v140 offset:3072
	ds_read_b128 v[200:203], v145
	ds_read_b128 v[204:207], v145 offset:1024
	ds_read_b128 v[208:211], v145 offset:2048
	ds_read_b128 v[212:215], v145 offset:3072
	ds_read_b128 v[216:219], v145 offset:4096
	ds_read_b128 v[220:223], v145 offset:5120
	ds_read_b128 v[224:227], v145 offset:6144
	ds_read_b128 v[228:231], v145 offset:7168
	s_add_i32 s54, s54, 1
	s_mul_i32 s40, s54, s53
	s_mul_hi_u32 s41, s54, s52
	s_add_i32 s41, s41, s40
	s_mul_i32 s40, s54, s52
	s_add_u32 s46, s40, s2
	s_addc_u32 s47, s41, s3
	v_mov_b64_e32 v[0:1], 0x580
	v_cmp_lt_i64_e64 s[40:41], s[46:47], v[0:1]
	v_mov_b64_e32 v[0:1], 0x57f
	v_cmp_gt_i64_e32 vcc, s[46:47], v[0:1]
	s_cbranch_vccnz .LBB0_330
	s_ashr_i32 s42, s46, 31
	s_lshr_b32 s42, s42, 29
	s_add_i32 s42, s46, s42
	s_ashr_i32 s43, s42, 3
	s_and_b32 s42, s42, -8
	s_sub_i32 s42, s46, s42
	s_cmp_lt_i32 s42, 0
	s_movk_i32 s44, 0xb1
	s_cselect_b32 s44, s44, 0xb0
	s_mul_i32 s42, s42, s44
	s_add_i32 s42, s42, s43
	s_mul_hi_i32 s43, s42, 0x2e8ba2e9
	s_lshr_b32 s44, s43, 31
	s_ashr_i32 s43, s43, 6
	s_add_i32 s43, s43, s44
	s_lshl_b32 s44, s43, 3
	s_sub_i32 s45, 32, s44
	s_min_i32 s45, s45, 8
	s_mulk_i32 s43, 0x160
	s_sub_i32 s43, s42, s43
	s_lshr_b32 s42, s43, 3
	s_and_b32 s43, s43, 7
	s_add_i32 s44, s44, s43
.LBB0_330:
	s_ashr_i32 s45, s44, 31
	s_lshl_b64 s[46:47], s[44:45], 20
	s_add_u32 s46, s12, s46
	s_addc_u32 s47, s13, s47
	s_and_b64 s[48:49], s[40:41], exec
	s_cselect_b32 s45, s47, s75
	s_cselect_b32 s59, s46, s74
	s_ashr_i32 s43, s42, 31
	s_lshl_b64 s[48:49], s[42:43], 20
	s_add_u32 s48, s14, s48
	s_addc_u32 s49, s0, s49
	s_and_b64 s[78:79], s[40:41], exec
	s_cselect_b32 s43, s49, s77
	s_cselect_b32 s63, s48, s76
	s_add_u32 s74, s74, 0x80080
	s_addc_u32 s75, s75, 0
	s_add_u32 s71, s76, 0x100
	v_mov_b32_e32 v0, 0
	s_addc_u32 s80, s77, 0
	s_mov_b32 s81, -2
	s_add_u32 s68, s74, 0xfff80080
	s_addc_u32 s69, s75, -1
	s_add_i32 s82, 0, 0x10000
	s_cmp_eq_u32 s81, 28
	s_cselect_b32 s79, s45, s69
	s_cselect_b32 s78, s59, s68
	s_cselect_b32 s77, s43, s80
	s_cselect_b32 s76, s63, s71
	s_add_i32 s68, 0, 0x14000
	v_lshl_add_u64 v[140:141], s[74:75], 0, v[136:137]
	s_add_i32 m0, s16, 0xc000
	global_load_lds_dwordx4 v[140:141], off
	v_lshl_add_u64 v[140:141], s[74:75], 0, v[138:139]
	s_add_i32 m0, s16, 0xe000
	s_nop 0
	global_load_lds_dwordx4 v[140:141], off
	s_waitcnt vmcnt(8)
	s_waitcnt lgkmcnt(0)
	s_setprio 1
	s_barrier
	v_mfma_f32_16x16x32_bf16 v[116:119], v[146:149], v[200:203], 0
	v_mfma_f32_16x16x32_bf16 v[112:115], v[160:163], v[200:203], 0
	v_mfma_f32_16x16x32_bf16 v[104:107], v[146:149], v[208:211], 0
	v_mfma_f32_16x16x32_bf16 v[96:99], v[160:163], v[208:211], 0
	v_mfma_f32_16x16x32_bf16 v[88:91], v[146:149], v[216:219], 0
	v_mfma_f32_16x16x32_bf16 v[80:83], v[160:163], v[216:219], 0
	v_mfma_f32_16x16x32_bf16 v[72:75], v[146:149], v[224:227], 0
	v_mfma_f32_16x16x32_bf16 v[64:67], v[160:163], v[224:227], 0
	v_mfma_f32_16x16x32_bf16 v[116:119], v[156:159], v[204:207], v[116:119]
	v_mfma_f32_16x16x32_bf16 v[112:115], v[164:167], v[204:207], v[112:115]
	v_mfma_f32_16x16x32_bf16 v[104:107], v[156:159], v[212:215], v[104:107]
	v_mfma_f32_16x16x32_bf16 v[96:99], v[164:167], v[212:215], v[96:99]
	v_mfma_f32_16x16x32_bf16 v[88:91], v[156:159], v[220:223], v[88:91]
	v_mfma_f32_16x16x32_bf16 v[80:83], v[164:167], v[220:223], v[80:83]
	v_mfma_f32_16x16x32_bf16 v[72:75], v[156:159], v[228:231], v[72:75]
	v_mfma_f32_16x16x32_bf16 v[64:67], v[164:167], v[228:231], v[64:67]
	v_mfma_f32_16x16x32_bf16 v[124:127], v[168:171], v[200:203], 0
	v_mfma_f32_16x16x32_bf16 v[120:123], v[192:195], v[200:203], 0
	v_mfma_f32_16x16x32_bf16 v[108:111], v[168:171], v[208:211], 0
	v_mfma_f32_16x16x32_bf16 v[100:103], v[192:195], v[208:211], 0
	v_mfma_f32_16x16x32_bf16 v[92:95], v[168:171], v[216:219], 0
	v_mfma_f32_16x16x32_bf16 v[84:87], v[192:195], v[216:219], 0
	v_mfma_f32_16x16x32_bf16 v[76:79], v[168:171], v[224:227], 0
	v_mfma_f32_16x16x32_bf16 v[68:71], v[192:195], v[224:227], 0
	v_mfma_f32_16x16x32_bf16 v[124:127], v[172:175], v[204:207], v[124:127]
	v_mfma_f32_16x16x32_bf16 v[120:123], v[196:199], v[204:207], v[120:123]
	v_mfma_f32_16x16x32_bf16 v[108:111], v[172:175], v[212:215], v[108:111]
	v_mfma_f32_16x16x32_bf16 v[100:103], v[196:199], v[212:215], v[100:103]
	v_mfma_f32_16x16x32_bf16 v[92:95], v[172:175], v[220:223], v[92:95]
	v_mfma_f32_16x16x32_bf16 v[84:87], v[196:199], v[220:223], v[84:87]
	v_mfma_f32_16x16x32_bf16 v[76:79], v[172:175], v[228:231], v[76:79]
	v_mfma_f32_16x16x32_bf16 v[68:71], v[196:199], v[228:231], v[68:71]
	s_barrier
	s_setprio 0
	s_add_i32 s69, s82, s15
	v_lshl_add_u64 v[140:141], s[76:77], 0, v[152:153]
	s_mov_b32 m0, s69
	ds_read_b128 v[200:203], v145 offset:16384
	ds_read_b128 v[204:207], v145 offset:17408
	ds_read_b128 v[208:211], v145 offset:18432
	ds_read_b128 v[212:215], v145 offset:19456
	ds_read_b128 v[216:219], v145 offset:20480
	ds_read_b128 v[220:223], v145 offset:21504
	ds_read_b128 v[224:227], v145 offset:22528
	ds_read_b128 v[228:231], v145 offset:23552
	global_load_lds_dwordx4 v[140:141], off
	s_add_i32 m0, s69, 0x2000
	s_add_u32 s82, s76, 0x80000
	v_lshl_add_u64 v[150:151], s[76:77], 0, v[128:129]
	s_addc_u32 s83, s77, 0
	s_add_i32 s68, s68, s15
	global_load_lds_dwordx4 v[150:151], off
	v_lshl_add_u64 v[182:183], s[82:83], 0, v[152:153]
	s_mov_b32 m0, s68
	v_lshl_add_u64 v[184:185], s[78:79], 0, v[130:131]
	global_load_lds_dwordx4 v[182:183], off
	v_lshl_add_u64 v[182:183], s[82:83], 0, v[128:129]
	s_add_i32 m0, s68, 0x2000
	s_nop 0
	global_load_lds_dwordx4 v[182:183], off
	v_lshl_add_u64 v[182:183], s[78:79], 0, v[132:133]
	s_mov_b32 m0, s16
	s_nop 0
	global_load_lds_dwordx4 v[182:183], off
	s_mov_b32 m0, s17
	s_nop 0
	global_load_lds_dwordx4 v[184:185], off
	s_waitcnt vmcnt(8)
	s_waitcnt lgkmcnt(0)
	s_setprio 1
	s_barrier
; #define PG8_STAGE(bufoff, gbase, voff) do { _Pragma("unroll") for (int _i = 0; _i < 2; ++_i) \
;         __builtin_amdgcn_global_load_lds((const unsigned*)((const char*)(gbase) + (voff)[_i]), (PG8_LAS unsigned*)(lds + (bufoff) + ldsw + _i * 8192), 16, 0, 0); } while (0)
; #define PG8_LDA(dst, b, h) do { _Pragma("unroll") for (int m = 0; m < 4; ++m) _Pragma("unroll") for (int k = 0; k < 2; ++k) dst[m][k] = *(const PG8_LAS bf16x8*)(lds + PG8_SA(b, h) + aoff + m * 2048 + k * 1024); } while (0)
; #define PG8_LDB(dst, b, h) do { _Pragma("unroll") for (int n = 0; n < 2; ++n) _Pragma("unroll") for (int k = 0; k < 2; ++k) dst[n][k] = *(const PG8_LAS bf16x8*)(lds + PG8_SB(b, h) + boff + n * 2048 + k * 1024); } while (0)
; #define PG8_MMA(ai, bj, At, Bt) do { __builtin_amdgcn_s_setprio(1); _Pragma("unroll") for (int m = 0; m < 4; ++m) _Pragma("unroll") for (int n = 0; n < 2; ++n) _Pragma("unroll") for (int k = 0; k < 2; ++k) \
;         acc[ai][bj][m][n] = __builtin_amdgcn_mfma_f32_16x16x32_bf16(Bt[n][k], At[m][k], acc[ai][bj][m][n], 0, 0, 0); __builtin_amdgcn_s_setprio(0); } while (0)
; #define PG8_WAIT_V(n) asm volatile("s_waitcnt vmcnt(" #n ")" ::: "memory")
; #define PG8_WAIT_L(n) asm volatile("s_waitcnt lgkmcnt(" #n ")" ::: "memory")
; #define PG8_BAR __builtin_amdgcn_s_barrier()
; #define PG8_SCHED __builtin_amdgcn_sched_barrier(0)
; template <class Epi, class Sched, bool ALIGN_EPI = false, bool SP2 = false>
; __device__ __forceinline__ void gemm_phase(PG8_LAS unsigned char* lds, const Gemm g, const Sched& S, const Epi& E) {
;     ...
;             PG8_WAIT_V(8); PG8_WAIT_L(0); PG8_BAR; PG8_MMA(1, 0, At, B0); PG8_MMA(1, 1, At, B1); PG8_BAR; PG8_SCHED;
;             PG8_LDB(B0, 1, 0); PG8_LDB(B1, 1, 1); PG8_SCHED; PG8_LDA(At, 1, 0); PG8_STAGE(PG8_SA(0, 1), a2 + hstep, voffA);
;             PG8_WAIT_V(8); PG8_WAIT_L(0); PG8_BAR; PG8_MMA(0, 0, At, B0); PG8_MMA(0, 1, At, B1); PG8_BAR; PG8_SCHED;
;             PG8_LDA(At, 1, 1); PG8_STAGE(PG8_SB(1, 0), b3, voffB); PG8_STAGE(PG8_SB(1, 1), b3 + hstep, voffB); PG8_STAGE(PG8_SA(1, 0), a3, voffA);
	v_mfma_f32_16x16x32_bf16 v[56:59], v[146:149], v[200:203], 0
	v_mfma_f32_16x16x32_bf16 v[48:51], v[160:163], v[200:203], 0
	v_mfma_f32_16x16x32_bf16 v[40:43], v[146:149], v[208:211], 0
	v_mfma_f32_16x16x32_bf16 v[32:35], v[160:163], v[208:211], 0
	v_mfma_f32_16x16x32_bf16 v[24:27], v[146:149], v[216:219], 0
	v_mfma_f32_16x16x32_bf16 v[16:19], v[160:163], v[216:219], 0
	v_mfma_f32_16x16x32_bf16 v[8:11], v[146:149], v[224:227], 0
	v_mfma_f32_16x16x32_bf16 v[4:7], v[160:163], v[224:227], 0
	v_mfma_f32_16x16x32_bf16 v[56:59], v[156:159], v[204:207], v[56:59]
	v_mfma_f32_16x16x32_bf16 v[48:51], v[164:167], v[204:207], v[48:51]
	v_mfma_f32_16x16x32_bf16 v[40:43], v[156:159], v[212:215], v[40:43]
	v_mfma_f32_16x16x32_bf16 v[32:35], v[164:167], v[212:215], v[32:35]
	v_mfma_f32_16x16x32_bf16 v[24:27], v[156:159], v[220:223], v[24:27]
	v_mfma_f32_16x16x32_bf16 v[16:19], v[164:167], v[220:223], v[16:19]
	v_mfma_f32_16x16x32_bf16 v[8:11], v[156:159], v[228:231], v[8:11]
	v_mfma_f32_16x16x32_bf16 v[4:7], v[164:167], v[228:231], v[4:7]
	v_mfma_f32_16x16x32_bf16 v[60:63], v[168:171], v[200:203], 0
	v_mfma_f32_16x16x32_bf16 v[52:55], v[192:195], v[200:203], 0
	v_mfma_f32_16x16x32_bf16 v[44:47], v[168:171], v[208:211], 0
	v_mfma_f32_16x16x32_bf16 v[36:39], v[192:195], v[208:211], 0
	v_mfma_f32_16x16x32_bf16 v[28:31], v[168:171], v[216:219], 0
	v_mfma_f32_16x16x32_bf16 v[20:23], v[192:195], v[216:219], 0
	v_mfma_f32_16x16x32_bf16 v[12:15], v[168:171], v[224:227], 0
	v_mfma_f32_16x16x32_bf16 v[0:3], v[192:195], v[224:227], 0
	v_mfma_f32_16x16x32_bf16 v[60:63], v[172:175], v[204:207], v[60:63]
	v_mfma_f32_16x16x32_bf16 v[52:55], v[196:199], v[204:207], v[52:55]
	v_mfma_f32_16x16x32_bf16 v[44:47], v[172:175], v[212:215], v[44:47]
	v_mfma_f32_16x16x32_bf16 v[36:39], v[196:199], v[212:215], v[36:39]
	v_mfma_f32_16x16x32_bf16 v[28:31], v[172:175], v[220:223], v[28:31]
	v_mfma_f32_16x16x32_bf16 v[20:23], v[196:199], v[220:223], v[20:23]
	v_mfma_f32_16x16x32_bf16 v[12:15], v[172:175], v[228:231], v[12:15]
	v_mfma_f32_16x16x32_bf16 v[0:3], v[196:199], v[228:231], v[0:3]
	s_barrier
	s_setprio 0
	v_add_u32_e32 v155, s93, v143
	s_add_i32 s68, 0, 0x1c000
	ds_read_b128 v[146:149], v155
	ds_read_b128 v[156:159], v155 offset:1024
	ds_read_b128 v[160:163], v155 offset:2048
	ds_read_b128 v[164:167], v155 offset:3072
	v_add_u32_e32 v155, s68, v143
	ds_read_b128 v[168:171], v155
	ds_read_b128 v[172:175], v155 offset:1024
	ds_read_b128 v[192:195], v155 offset:2048
	ds_read_b128 v[196:199], v155 offset:3072
	s_add_u32 s78, s78, 0x80000
	s_addc_u32 s79, s79, 0
	s_mov_b32 m0, s22
	v_lshl_add_u64 v[188:189], s[78:79], 0, v[132:133]
	ds_read_b128 v[200:203], v145 offset:32768
	ds_read_b128 v[204:207], v145 offset:33792
	ds_read_b128 v[208:211], v145 offset:34816
	ds_read_b128 v[212:215], v145 offset:35840
	ds_read_b128 v[216:219], v145 offset:36864
	ds_read_b128 v[220:223], v145 offset:37888
	ds_read_b128 v[224:227], v145 offset:38912
	ds_read_b128 v[228:231], v145 offset:39936
	global_load_lds_dwordx4 v[188:189], off
	v_lshl_add_u64 v[188:189], s[78:79], 0, v[130:131]
	s_mov_b32 m0, s23
	s_nop 0
	global_load_lds_dwordx4 v[188:189], off
	s_waitcnt vmcnt(8)
	s_waitcnt lgkmcnt(0)
	s_setprio 1
	s_barrier
	v_mfma_f32_16x16x32_bf16 v[116:119], v[146:149], v[200:203], v[116:119]
	v_mfma_f32_16x16x32_bf16 v[112:115], v[160:163], v[200:203], v[112:115]
	v_mfma_f32_16x16x32_bf16 v[104:107], v[146:149], v[208:211], v[104:107]
	v_mfma_f32_16x16x32_bf16 v[96:99], v[160:163], v[208:211], v[96:99]
	v_mfma_f32_16x16x32_bf16 v[88:91], v[146:149], v[216:219], v[88:91]
	v_mfma_f32_16x16x32_bf16 v[80:83], v[160:163], v[216:219], v[80:83]
	v_mfma_f32_16x16x32_bf16 v[72:75], v[146:149], v[224:227], v[72:75]
	v_mfma_f32_16x16x32_bf16 v[64:67], v[160:163], v[224:227], v[64:67]
	v_mfma_f32_16x16x32_bf16 v[116:119], v[156:159], v[204:207], v[116:119]
	v_mfma_f32_16x16x32_bf16 v[112:115], v[164:167], v[204:207], v[112:115]
	v_mfma_f32_16x16x32_bf16 v[104:107], v[156:159], v[212:215], v[104:107]
	v_mfma_f32_16x16x32_bf16 v[96:99], v[164:167], v[212:215], v[96:99]
	v_mfma_f32_16x16x32_bf16 v[88:91], v[156:159], v[220:223], v[88:91]
	v_mfma_f32_16x16x32_bf16 v[80:83], v[164:167], v[220:223], v[80:83]
	v_mfma_f32_16x16x32_bf16 v[72:75], v[156:159], v[228:231], v[72:75]
	v_mfma_f32_16x16x32_bf16 v[64:67], v[164:167], v[228:231], v[64:67]
	v_mfma_f32_16x16x32_bf16 v[124:127], v[168:171], v[200:203], v[124:127]
	v_mfma_f32_16x16x32_bf16 v[120:123], v[192:195], v[200:203], v[120:123]
	v_mfma_f32_16x16x32_bf16 v[108:111], v[168:171], v[208:211], v[108:111]
	v_mfma_f32_16x16x32_bf16 v[100:103], v[192:195], v[208:211], v[100:103]
	v_mfma_f32_16x16x32_bf16 v[92:95], v[168:171], v[216:219], v[92:95]
	v_mfma_f32_16x16x32_bf16 v[84:87], v[192:195], v[216:219], v[84:87]
	v_mfma_f32_16x16x32_bf16 v[76:79], v[168:171], v[224:227], v[76:79]
	v_mfma_f32_16x16x32_bf16 v[68:71], v[192:195], v[224:227], v[68:71]
	v_mfma_f32_16x16x32_bf16 v[124:127], v[172:175], v[204:207], v[124:127]
	v_mfma_f32_16x16x32_bf16 v[120:123], v[196:199], v[204:207], v[120:123]
	v_mfma_f32_16x16x32_bf16 v[108:111], v[172:175], v[212:215], v[108:111]
	v_mfma_f32_16x16x32_bf16 v[100:103], v[196:199], v[212:215], v[100:103]
	v_mfma_f32_16x16x32_bf16 v[92:95], v[172:175], v[220:223], v[92:95]
	v_mfma_f32_16x16x32_bf16 v[84:87], v[196:199], v[220:223], v[84:87]
	v_mfma_f32_16x16x32_bf16 v[76:79], v[172:175], v[228:231], v[76:79]
	v_mfma_f32_16x16x32_bf16 v[68:71], v[196:199], v[228:231], v[68:71]
	s_barrier
; #define PG8_STAGE(bufoff, gbase, voff) do { _Pragma("unroll") for (int _i = 0; _i < 2; ++_i) \
;         __builtin_amdgcn_global_load_lds((const unsigned*)((const char*)(gbase) + (voff)[_i]), (PG8_LAS unsigned*)(lds + (bufoff) + ldsw + _i * 8192), 16, 0, 0); } while (0)
; #define PG8_LDA(dst, b, h) do { _Pragma("unroll") for (int m = 0; m < 4; ++m) _Pragma("unroll") for (int k = 0; k < 2; ++k) dst[m][k] = *(const PG8_LAS bf16x8*)(lds + PG8_SA(b, h) + aoff + m * 2048 + k * 1024); } while (0)
; #define PG8_MMA(ai, bj, At, Bt) do { __builtin_amdgcn_s_setprio(1); _Pragma("unroll") for (int m = 0; m < 4; ++m) _Pragma("unroll") for (int n = 0; n < 2; ++n) _Pragma("unroll") for (int k = 0; k < 2; ++k) \
;         acc[ai][bj][m][n] = __builtin_amdgcn_mfma_f32_16x16x32_bf16(Bt[n][k], At[m][k], acc[ai][bj][m][n], 0, 0, 0); __builtin_amdgcn_s_setprio(0); } while (0)
; #define PG8_WAIT_V(n) asm volatile("s_waitcnt vmcnt(" #n ")" ::: "memory")
; #define PG8_WAIT_L(n) asm volatile("s_waitcnt lgkmcnt(" #n ")" ::: "memory")
; #define PG8_BAR __builtin_amdgcn_s_barrier()
; #define PG8_SCHED __builtin_amdgcn_sched_barrier(0)
; template <class Epi, class Sched, bool ALIGN_EPI = false, bool SP2 = false>
; __device__ __forceinline__ void gemm_phase(PG8_LAS unsigned char* lds, const Gemm g, const Sched& S, const Epi& E) {
;     ...
;         for (int t = 0; t < nt; t += 2) {
;             const bool last = (t == nt - 2);
;     ...
;             PG8_LDA(At, 1, 1); PG8_STAGE(PG8_SB(1, 0), b3, voffB); PG8_STAGE(PG8_SB(1, 1), b3 + hstep, voffB); PG8_STAGE(PG8_SA(1, 0), a3, voffA);
;             PG8_WAIT_V(8); PG8_WAIT_L(0); PG8_BAR; PG8_MMA(1, 0, At, B0); PG8_MMA(1, 1, At, B1); PG8_BAR; PG8_SCHED;
	s_setprio 0
	s_add_i32 s69, s93, s15
	v_lshl_add_u64 v[140:141], v[140:141], 0, s[18:19]
	s_mov_b32 m0, s69
	ds_read_b128 v[200:203], v145 offset:49152
	ds_read_b128 v[204:207], v145 offset:50176
	ds_read_b128 v[208:211], v145 offset:51200
	ds_read_b128 v[212:215], v145 offset:52224
	ds_read_b128 v[216:219], v145 offset:53248
	ds_read_b128 v[220:223], v145 offset:54272
	ds_read_b128 v[224:227], v145 offset:55296
	ds_read_b128 v[228:231], v145 offset:56320
	global_load_lds_dwordx4 v[140:141], off
	s_add_i32 m0, s69, 0x2000
	s_add_u32 s76, s76, 0x80080
	v_lshl_add_u64 v[140:141], v[150:151], 0, s[18:19]
	s_addc_u32 s77, s77, 0
	s_add_i32 s68, s68, s15
	global_load_lds_dwordx4 v[140:141], off
	v_lshl_add_u64 v[140:141], s[76:77], 0, v[152:153]
	s_mov_b32 m0, s68
	s_nop 0
	global_load_lds_dwordx4 v[140:141], off
	v_lshl_add_u64 v[140:141], s[76:77], 0, v[128:129]
	s_add_i32 m0, s68, 0x2000
	s_nop 0
	global_load_lds_dwordx4 v[140:141], off
	v_lshl_add_u64 v[140:141], v[182:183], 0, s[18:19]
	s_mov_b32 m0, s26
	s_nop 0
	global_load_lds_dwordx4 v[140:141], off
	v_lshl_add_u64 v[140:141], v[184:185], 0, s[18:19]
	s_mov_b32 m0, s34
	s_nop 0
	global_load_lds_dwordx4 v[140:141], off
	s_waitcnt vmcnt(8)
	s_waitcnt lgkmcnt(0)
	s_setprio 1
	s_barrier
	v_mfma_f32_16x16x32_bf16 v[56:59], v[146:149], v[200:203], v[56:59]
	v_mfma_f32_16x16x32_bf16 v[48:51], v[160:163], v[200:203], v[48:51]
	v_mfma_f32_16x16x32_bf16 v[40:43], v[146:149], v[208:211], v[40:43]
	v_mfma_f32_16x16x32_bf16 v[32:35], v[160:163], v[208:211], v[32:35]
	v_mfma_f32_16x16x32_bf16 v[24:27], v[146:149], v[216:219], v[24:27]
	v_mfma_f32_16x16x32_bf16 v[16:19], v[160:163], v[216:219], v[16:19]
	v_mfma_f32_16x16x32_bf16 v[8:11], v[146:149], v[224:227], v[8:11]
	v_mfma_f32_16x16x32_bf16 v[4:7], v[160:163], v[224:227], v[4:7]
	v_mfma_f32_16x16x32_bf16 v[56:59], v[156:159], v[204:207], v[56:59]
	v_mfma_f32_16x16x32_bf16 v[48:51], v[164:167], v[204:207], v[48:51]
	v_mfma_f32_16x16x32_bf16 v[40:43], v[156:159], v[212:215], v[40:43]
	v_mfma_f32_16x16x32_bf16 v[32:35], v[164:167], v[212:215], v[32:35]
	v_mfma_f32_16x16x32_bf16 v[24:27], v[156:159], v[220:223], v[24:27]
	v_mfma_f32_16x16x32_bf16 v[16:19], v[164:167], v[220:223], v[16:19]
	v_mfma_f32_16x16x32_bf16 v[8:11], v[156:159], v[228:231], v[8:11]
	v_mfma_f32_16x16x32_bf16 v[4:7], v[164:167], v[228:231], v[4:7]
	v_mfma_f32_16x16x32_bf16 v[60:63], v[168:171], v[200:203], v[60:63]
	v_mfma_f32_16x16x32_bf16 v[52:55], v[192:195], v[200:203], v[52:55]
	v_mfma_f32_16x16x32_bf16 v[44:47], v[168:171], v[208:211], v[44:47]
	v_mfma_f32_16x16x32_bf16 v[36:39], v[192:195], v[208:211], v[36:39]
	v_mfma_f32_16x16x32_bf16 v[28:31], v[168:171], v[216:219], v[28:31]
	v_mfma_f32_16x16x32_bf16 v[20:23], v[192:195], v[216:219], v[20:23]
	v_mfma_f32_16x16x32_bf16 v[12:15], v[168:171], v[224:227], v[12:15]
	v_mfma_f32_16x16x32_bf16 v[0:3], v[192:195], v[224:227], v[0:3]
	v_mfma_f32_16x16x32_bf16 v[60:63], v[172:175], v[204:207], v[60:63]
	v_mfma_f32_16x16x32_bf16 v[52:55], v[196:199], v[204:207], v[52:55]
	v_mfma_f32_16x16x32_bf16 v[44:47], v[172:175], v[212:215], v[44:47]
	v_mfma_f32_16x16x32_bf16 v[36:39], v[196:199], v[212:215], v[36:39]
	v_mfma_f32_16x16x32_bf16 v[28:31], v[172:175], v[220:223], v[28:31]
	v_mfma_f32_16x16x32_bf16 v[20:23], v[196:199], v[220:223], v[20:23]
	v_mfma_f32_16x16x32_bf16 v[12:15], v[172:175], v[228:231], v[12:15]
	v_mfma_f32_16x16x32_bf16 v[0:3], v[196:199], v[228:231], v[0:3]
	s_barrier
	s_setprio 0
	s_add_i32 s81, s81, 2
	s_add_u32 s74, s74, 0x100
	s_addc_u32 s75, s75, 0
	s_add_u32 s71, s71, 0x100
	s_addc_u32 s80, s80, 0
	s_cmp_gt_u32 s81, 29
	s_cbranch_scc1 .Lpeel_exit_331
